# v31: v30 + int8 GEMM1 epilogue scales prefetched during the unit's last K-iteration (counted waits), epilogue start no longer drains vmcnt(0)
# baseline (speedup 1.0000x reference)
.LBB0_300:
	s_add_u32 s100, s0, 0xfff80000
	s_addc_u32 s101, s1, -1
	s_add_u32 s28, s0, 0xfff80080
	s_addc_u32 s29, s1, -1
	s_add_i32 s42, 0, 0x10000
	s_cmp_eq_u32 s41, 28
	s_cselect_b32 s31, s18, s29
	s_cselect_b32 s30, s19, s28
	v_add_u32_e32 v0, s42, v199
	s_cselect_b32 s29, s27, s40
	s_cselect_b32 s28, s34, s35
	s_add_i32 s49, 0, 0x14000
	ds_read_b128 v[2:5], v0
	ds_read_b128 v[6:9], v0 offset:1024
	ds_read_b128 v[10:13], v0 offset:2048
	ds_read_b128 v[14:17], v0 offset:3072
	v_add_u32_e32 v0, s49, v199
	ds_read_b128 v[146:149], v0
	ds_read_b128 v[150:153], v0 offset:1024
	ds_read_b128 v[154:157], v0 offset:2048
	ds_read_b128 v[158:161], v0 offset:3072
	s_mov_b32 m0, s15
	ds_read_b128 v[174:177], v250
	ds_read_b128 v[178:181], v250 offset:1024
	ds_read_b128 v[182:185], v250 offset:2048
	ds_read_b128 v[186:189], v250 offset:3072
	ds_read_b128 v[190:193], v250 offset:4096
	ds_read_b128 v[200:203], v250 offset:5120
	ds_read_b128 v[204:207], v250 offset:6144
	ds_read_b128 v[208:211], v250 offset:7168
	global_load_lds_dwordx4 v162, s[100:101]
	s_mov_b32 m0, s88
	s_nop 0
	global_load_lds_dwordx4 v166, s[100:101]
	s_add_i32 m0, s21, 0xc000
	s_nop 0
	global_load_lds_dwordx4 v170, s[0:1]
	s_add_i32 m0, s21, 0xe000
	s_nop 0
	global_load_lds_dwordx4 v172, s[0:1]
	s_cmp_eq_u32 s41, 28
	s_cbranch_scc1 .Lspf_w0
	s_waitcnt vmcnt(8)
	s_branch .Lspf_j0
.Lspf_w0:
	v_mbcnt_lo_u32_b32 v244, -1, 0
	v_mbcnt_hi_u32_b32 v244, -1, v244
	s_lshl_b32 s98, s20, 8
	s_add_i32 s98, s98, s77
	v_and_or_b32 v245, v244, 15, s98
	v_lshlrev_b32_e32 v245, 2, v245
	v_ashrrev_i32_e32 v244, 4, v244
	v_lshlrev_b32_e32 v244, 5, v244
	s_lshl_b32 s98, s56, 8
	s_ashr_i32 s99, s98, 31
	s_lshl_b64 s[98:99], s[98:99], 2
	s_add_u32 s98, s66, s98
	s_addc_u32 s99, s67, s99
	global_load_dwordx4 v[220:223], v244, s[98:99] offset:16
	global_load_dwordx4 v[224:227], v244, s[98:99]
	global_load_dwordx4 v[228:231], v244, s[98:99] offset:528
	global_load_dwordx4 v[232:235], v244, s[98:99] offset:512
	global_load_dword v236, v245, s[86:87]
	global_load_dword v237, v245, s[86:87] offset:64
	global_load_dword v238, v245, s[86:87] offset:128
	global_load_dword v239, v245, s[86:87] offset:192
	global_load_dword v240, v245, s[86:87] offset:512
	global_load_dword v241, v245, s[86:87] offset:576
	global_load_dword v242, v245, s[86:87] offset:640
	global_load_dword v243, v245, s[86:87] offset:704
	s_waitcnt vmcnt(20)
.Lspf_j0:
	s_waitcnt lgkmcnt(0)
	s_barrier
	s_waitcnt lgkmcnt(0)
	v_mfma_i32_16x16x64_i8 v[142:145], v[2:5], v[174:177], v[142:145]
	v_mfma_i32_16x16x64_i8 v[142:145], v[6:9], v[178:181], v[142:145]
	v_mfma_i32_16x16x64_i8 v[134:137], v[2:5], v[182:185], v[134:137]
	v_mfma_i32_16x16x64_i8 v[134:137], v[6:9], v[186:189], v[134:137]
	v_mfma_i32_16x16x64_i8 v[122:125], v[2:5], v[190:193], v[122:125]
	v_mfma_i32_16x16x64_i8 v[122:125], v[6:9], v[200:203], v[122:125]
	v_mfma_i32_16x16x64_i8 v[106:109], v[2:5], v[204:207], v[106:109]
	v_mfma_i32_16x16x64_i8 v[106:109], v[6:9], v[208:211], v[106:109]
	v_mfma_i32_16x16x64_i8 v[138:141], v[10:13], v[174:177], v[138:141]
	v_mfma_i32_16x16x64_i8 v[138:141], v[14:17], v[178:181], v[138:141]
	v_mfma_i32_16x16x64_i8 v[130:133], v[10:13], v[182:185], v[130:133]
	v_mfma_i32_16x16x64_i8 v[130:133], v[14:17], v[186:189], v[130:133]
	v_mfma_i32_16x16x64_i8 v[114:117], v[10:13], v[190:193], v[114:117]
	v_mfma_i32_16x16x64_i8 v[114:117], v[14:17], v[200:203], v[114:117]
	v_mfma_i32_16x16x64_i8 v[98:101], v[10:13], v[204:207], v[98:101]
	v_mfma_i32_16x16x64_i8 v[98:101], v[14:17], v[208:211], v[98:101]
	v_mfma_i32_16x16x64_i8 v[126:129], v[146:149], v[174:177], v[126:129]
	v_mfma_i32_16x16x64_i8 v[126:129], v[150:153], v[178:181], v[126:129]
	v_mfma_i32_16x16x64_i8 v[110:113], v[146:149], v[182:185], v[110:113]
	v_mfma_i32_16x16x64_i8 v[110:113], v[150:153], v[186:189], v[110:113]
	v_mfma_i32_16x16x64_i8 v[94:97], v[146:149], v[190:193], v[94:97]
	v_mfma_i32_16x16x64_i8 v[94:97], v[150:153], v[200:203], v[94:97]
	v_mfma_i32_16x16x64_i8 v[86:89], v[146:149], v[204:207], v[86:89]
	v_mfma_i32_16x16x64_i8 v[86:89], v[150:153], v[208:211], v[86:89]
	v_mfma_i32_16x16x64_i8 v[118:121], v[154:157], v[174:177], v[118:121]
	v_mfma_i32_16x16x64_i8 v[118:121], v[158:161], v[178:181], v[118:121]
	v_mfma_i32_16x16x64_i8 v[102:105], v[154:157], v[182:185], v[102:105]
	v_mfma_i32_16x16x64_i8 v[102:105], v[158:161], v[186:189], v[102:105]
	v_mfma_i32_16x16x64_i8 v[90:93], v[154:157], v[190:193], v[90:93]
	v_mfma_i32_16x16x64_i8 v[90:93], v[158:161], v[200:203], v[90:93]
	v_mfma_i32_16x16x64_i8 v[82:85], v[154:157], v[204:207], v[82:85]
	v_mfma_i32_16x16x64_i8 v[82:85], v[158:161], v[208:211], v[82:85]
	s_barrier
	s_add_i32 s42, s42, s81
	s_mov_b32 m0, s42
	ds_read_b128 v[174:177], v250 offset:16384
	ds_read_b128 v[178:181], v250 offset:17408
	ds_read_b128 v[182:185], v250 offset:18432
	ds_read_b128 v[186:189], v250 offset:19456
	ds_read_b128 v[190:193], v250 offset:20480
	ds_read_b128 v[200:203], v250 offset:21504
	ds_read_b128 v[204:207], v250 offset:22528
	ds_read_b128 v[208:211], v250 offset:23552
	global_load_lds_dwordx4 v164, s[28:29]
	s_add_i32 m0, s42, 0x2000
	s_add_u32 s42, s28, 0x80000
	s_addc_u32 s43, s29, 0
	s_add_i32 s49, s49, s81
	global_load_lds_dwordx4 v168, s[28:29]
	s_mov_b32 m0, s49
	s_nop 0
	global_load_lds_dwordx4 v164, s[42:43]
	s_add_i32 m0, s49, 0x2000
	s_nop 0
	global_load_lds_dwordx4 v168, s[42:43]
	s_cmp_eq_u32 s41, 28
	s_cbranch_scc1 .Lspf_w1
	s_waitcnt vmcnt(6)
	s_branch .Lspf_j1
.Lspf_w1:
	s_waitcnt vmcnt(18)
.Lspf_j1:
	s_waitcnt lgkmcnt(0)
	s_barrier
	s_waitcnt lgkmcnt(0)
	v_mfma_i32_16x16x64_i8 v[78:81], v[2:5], v[174:177], v[78:81]
	v_mfma_i32_16x16x64_i8 v[78:81], v[6:9], v[178:181], v[78:81]
	v_mfma_i32_16x16x64_i8 v[74:77], v[10:13], v[174:177], v[74:77]
	v_mfma_i32_16x16x64_i8 v[74:77], v[14:17], v[178:181], v[74:77]
	v_mfma_i32_16x16x64_i8 v[70:73], v[2:5], v[182:185], v[70:73]
	v_mfma_i32_16x16x64_i8 v[70:73], v[6:9], v[186:189], v[70:73]
	v_mfma_i32_16x16x64_i8 v[66:69], v[10:13], v[182:185], v[66:69]
	v_mfma_i32_16x16x64_i8 v[66:69], v[14:17], v[186:189], v[66:69]
	v_mfma_i32_16x16x64_i8 v[54:57], v[2:5], v[190:193], v[54:57]
	v_mfma_i32_16x16x64_i8 v[54:57], v[6:9], v[200:203], v[54:57]
	v_mfma_i32_16x16x64_i8 v[50:53], v[10:13], v[190:193], v[50:53]
	v_mfma_i32_16x16x64_i8 v[50:53], v[14:17], v[200:203], v[50:53]
	v_mfma_i32_16x16x64_i8 v[2:5], v[2:5], v[204:207], v[38:41]
	v_mfma_i32_16x16x64_i8 v[2:5], v[6:9], v[208:211], v[2:5]
	v_mfma_i32_16x16x64_i8 v[6:9], v[10:13], v[204:207], v[34:37]
	v_mfma_i32_16x16x64_i8 v[6:9], v[14:17], v[208:211], v[6:9]
	v_mfma_i32_16x16x64_i8 v[34:37], v[146:149], v[182:185], v[46:49]
	v_mfma_i32_16x16x64_i8 v[46:49], v[150:153], v[186:189], v[34:37]
	v_mfma_i32_16x16x64_i8 v[34:37], v[154:157], v[182:185], v[42:45]
	v_mfma_i32_16x16x64_i8 v[42:45], v[158:161], v[186:189], v[34:37]
	v_mfma_i32_16x16x64_i8 v[30:33], v[146:149], v[190:193], v[30:33]
	v_mfma_i32_16x16x64_i8 v[30:33], v[150:153], v[200:203], v[30:33]
	v_mfma_i32_16x16x64_i8 v[26:29], v[154:157], v[190:193], v[26:29]
	v_mfma_i32_16x16x64_i8 v[26:29], v[158:161], v[200:203], v[26:29]
	v_mfma_i32_16x16x64_i8 v[22:25], v[146:149], v[204:207], v[22:25]
	v_mfma_i32_16x16x64_i8 v[22:25], v[150:153], v[208:211], v[22:25]
	v_mfma_i32_16x16x64_i8 v[18:21], v[154:157], v[204:207], v[18:21]
	v_mfma_i32_16x16x64_i8 v[18:21], v[158:161], v[208:211], v[18:21]
	v_mfma_i32_16x16x64_i8 v[10:13], v[146:149], v[174:177], v[62:65]
	v_mfma_i32_16x16x64_i8 v[10:13], v[150:153], v[178:181], v[10:13]
	v_mfma_i32_16x16x64_i8 v[14:17], v[154:157], v[174:177], v[58:61]
	v_mfma_i32_16x16x64_i8 v[14:17], v[158:161], v[178:181], v[14:17]
	s_barrier
	s_add_i32 s42, 0, 0x18000
	v_add_u32_e32 v0, s42, v199
	s_add_i32 s43, 0, 0x1c000
	ds_read_b128 v[34:37], v0
	ds_read_b128 v[38:41], v0 offset:1024
	ds_read_b128 v[58:61], v0 offset:2048
	ds_read_b128 v[62:65], v0 offset:3072
	v_add_u32_e32 v0, s43, v199
	ds_read_b128 v[146:149], v0
	ds_read_b128 v[150:153], v0 offset:1024
	ds_read_b128 v[154:157], v0 offset:2048
	ds_read_b128 v[158:161], v0 offset:3072
	s_mov_b32 m0, s21
	ds_read_b128 v[174:177], v250 offset:32768
	ds_read_b128 v[178:181], v250 offset:33792
	ds_read_b128 v[182:185], v250 offset:34816
	ds_read_b128 v[186:189], v250 offset:35840
	ds_read_b128 v[190:193], v250 offset:36864
	ds_read_b128 v[200:203], v250 offset:37888
	ds_read_b128 v[204:207], v250 offset:38912
	ds_read_b128 v[208:211], v250 offset:39936
	global_load_lds_dwordx4 v162, s[30:31]
	s_mov_b32 m0, s57
	s_nop 0
	global_load_lds_dwordx4 v166, s[30:31]
	s_add_u32 s30, s30, 0x80000
	s_addc_u32 s31, s31, 0
	s_mov_b32 m0, s73
	s_nop 0
	global_load_lds_dwordx4 v162, s[30:31]
	s_mov_b32 m0, s76
	s_nop 0
	global_load_lds_dwordx4 v166, s[30:31]
	s_cmp_eq_u32 s41, 28
	s_cbranch_scc1 .Lspf_w2
	s_waitcnt vmcnt(8)
	s_branch .Lspf_j2
.Lspf_w2:
	s_waitcnt vmcnt(20)
.Lspf_j2:
	s_waitcnt lgkmcnt(0)
	s_barrier
	s_waitcnt lgkmcnt(0)
	v_mfma_i32_16x16x64_i8 v[142:145], v[34:37], v[174:177], v[142:145]
	v_mfma_i32_16x16x64_i8 v[142:145], v[38:41], v[178:181], v[142:145]
	v_mfma_i32_16x16x64_i8 v[134:137], v[34:37], v[182:185], v[134:137]
	v_mfma_i32_16x16x64_i8 v[134:137], v[38:41], v[186:189], v[134:137]
	v_mfma_i32_16x16x64_i8 v[122:125], v[34:37], v[190:193], v[122:125]
	v_mfma_i32_16x16x64_i8 v[122:125], v[38:41], v[200:203], v[122:125]
	v_mfma_i32_16x16x64_i8 v[106:109], v[34:37], v[204:207], v[106:109]
	v_mfma_i32_16x16x64_i8 v[106:109], v[38:41], v[208:211], v[106:109]
	v_mfma_i32_16x16x64_i8 v[138:141], v[58:61], v[174:177], v[138:141]
	v_mfma_i32_16x16x64_i8 v[138:141], v[62:65], v[178:181], v[138:141]
	v_mfma_i32_16x16x64_i8 v[130:133], v[58:61], v[182:185], v[130:133]
	v_mfma_i32_16x16x64_i8 v[130:133], v[62:65], v[186:189], v[130:133]
	v_mfma_i32_16x16x64_i8 v[114:117], v[58:61], v[190:193], v[114:117]
	v_mfma_i32_16x16x64_i8 v[114:117], v[62:65], v[200:203], v[114:117]
	v_mfma_i32_16x16x64_i8 v[98:101], v[58:61], v[204:207], v[98:101]
	v_mfma_i32_16x16x64_i8 v[98:101], v[62:65], v[208:211], v[98:101]
	v_mfma_i32_16x16x64_i8 v[126:129], v[146:149], v[174:177], v[126:129]
	v_mfma_i32_16x16x64_i8 v[126:129], v[150:153], v[178:181], v[126:129]
	v_mfma_i32_16x16x64_i8 v[110:113], v[146:149], v[182:185], v[110:113]
	v_mfma_i32_16x16x64_i8 v[110:113], v[150:153], v[186:189], v[110:113]
	v_mfma_i32_16x16x64_i8 v[94:97], v[146:149], v[190:193], v[94:97]
	v_mfma_i32_16x16x64_i8 v[94:97], v[150:153], v[200:203], v[94:97]
	v_mfma_i32_16x16x64_i8 v[86:89], v[146:149], v[204:207], v[86:89]
	v_mfma_i32_16x16x64_i8 v[86:89], v[150:153], v[208:211], v[86:89]
	v_mfma_i32_16x16x64_i8 v[118:121], v[154:157], v[174:177], v[118:121]
	v_mfma_i32_16x16x64_i8 v[118:121], v[158:161], v[178:181], v[118:121]
	v_mfma_i32_16x16x64_i8 v[102:105], v[154:157], v[182:185], v[102:105]
	v_mfma_i32_16x16x64_i8 v[102:105], v[158:161], v[186:189], v[102:105]
	v_mfma_i32_16x16x64_i8 v[90:93], v[154:157], v[190:193], v[90:93]
	v_mfma_i32_16x16x64_i8 v[90:93], v[158:161], v[200:203], v[90:93]
	v_mfma_i32_16x16x64_i8 v[82:85], v[154:157], v[204:207], v[82:85]
	v_mfma_i32_16x16x64_i8 v[82:85], v[158:161], v[208:211], v[82:85]
	s_barrier
	s_add_i32 s30, s42, s81
	s_add_u32 s98, s28, 0x80
	s_addc_u32 s99, s29, 0
	s_mov_b32 m0, s30
	ds_read_b128 v[174:177], v250 offset:49152
	ds_read_b128 v[178:181], v250 offset:50176
	ds_read_b128 v[182:185], v250 offset:51200
	ds_read_b128 v[186:189], v250 offset:52224
	ds_read_b128 v[190:193], v250 offset:53248
	ds_read_b128 v[200:203], v250 offset:54272
	ds_read_b128 v[204:207], v250 offset:55296
	ds_read_b128 v[208:211], v250 offset:56320
	global_load_lds_dwordx4 v164, s[98:99]
	s_add_i32 m0, s30, 0x2000
	s_add_u32 s28, s28, 0x80080
	s_addc_u32 s29, s29, 0
	s_add_i32 s30, s43, s81
	global_load_lds_dwordx4 v168, s[98:99]
	s_mov_b32 m0, s30
	s_nop 0
	global_load_lds_dwordx4 v164, s[28:29]
	s_add_i32 m0, s30, 0x2000
	s_nop 0
	global_load_lds_dwordx4 v168, s[28:29]
	s_waitcnt vmcnt(6)
	s_waitcnt lgkmcnt(0)
	s_barrier
	s_waitcnt lgkmcnt(0)
	v_mfma_i32_16x16x64_i8 v[78:81], v[34:37], v[174:177], v[78:81]
	v_mfma_i32_16x16x64_i8 v[78:81], v[38:41], v[178:181], v[78:81]
	v_mfma_i32_16x16x64_i8 v[70:73], v[34:37], v[182:185], v[70:73]
	v_mfma_i32_16x16x64_i8 v[70:73], v[38:41], v[186:189], v[70:73]
	v_mfma_i32_16x16x64_i8 v[54:57], v[34:37], v[190:193], v[54:57]
	v_mfma_i32_16x16x64_i8 v[54:57], v[38:41], v[200:203], v[54:57]
	v_mfma_i32_16x16x64_i8 v[2:5], v[34:37], v[204:207], v[2:5]
	v_mfma_i32_16x16x64_i8 v[38:41], v[38:41], v[208:211], v[2:5]
	v_mfma_i32_16x16x64_i8 v[74:77], v[58:61], v[174:177], v[74:77]
	v_mfma_i32_16x16x64_i8 v[74:77], v[62:65], v[178:181], v[74:77]
	v_mfma_i32_16x16x64_i8 v[66:69], v[58:61], v[182:185], v[66:69]
	v_mfma_i32_16x16x64_i8 v[66:69], v[62:65], v[186:189], v[66:69]
	v_mfma_i32_16x16x64_i8 v[50:53], v[58:61], v[190:193], v[50:53]
	v_mfma_i32_16x16x64_i8 v[50:53], v[62:65], v[200:203], v[50:53]
	v_mfma_i32_16x16x64_i8 v[2:5], v[58:61], v[204:207], v[6:9]
	v_mfma_i32_16x16x64_i8 v[34:37], v[62:65], v[208:211], v[2:5]
	v_mfma_i32_16x16x64_i8 v[2:5], v[146:149], v[174:177], v[10:13]
	v_mfma_i32_16x16x64_i8 v[62:65], v[150:153], v[178:181], v[2:5]
	v_mfma_i32_16x16x64_i8 v[2:5], v[154:157], v[174:177], v[14:17]
	v_mfma_i32_16x16x64_i8 v[58:61], v[158:161], v[178:181], v[2:5]
	v_mfma_i32_16x16x64_i8 v[2:5], v[146:149], v[182:185], v[46:49]
	v_mfma_i32_16x16x64_i8 v[46:49], v[150:153], v[186:189], v[2:5]
	v_mfma_i32_16x16x64_i8 v[2:5], v[154:157], v[182:185], v[42:45]
	v_mfma_i32_16x16x64_i8 v[42:45], v[158:161], v[186:189], v[2:5]
	v_mfma_i32_16x16x64_i8 v[2:5], v[146:149], v[190:193], v[30:33]
	v_mfma_i32_16x16x64_i8 v[30:33], v[150:153], v[200:203], v[2:5]
	v_mfma_i32_16x16x64_i8 v[2:5], v[154:157], v[190:193], v[26:29]
	v_mfma_i32_16x16x64_i8 v[26:29], v[158:161], v[200:203], v[2:5]
	v_mfma_i32_16x16x64_i8 v[2:5], v[146:149], v[204:207], v[22:25]
	v_mfma_i32_16x16x64_i8 v[22:25], v[150:153], v[208:211], v[2:5]
	v_mfma_i32_16x16x64_i8 v[2:5], v[154:157], v[204:207], v[18:21]
	v_mfma_i32_16x16x64_i8 v[18:21], v[158:161], v[208:211], v[2:5]
	s_barrier
	s_add_i32 s41, s41, 2
	s_add_u32 s0, s0, 0x100
	s_addc_u32 s1, s1, 0
	s_add_u32 s35, s35, 0x100
	s_addc_u32 s40, s40, 0
	s_cmp_gt_u32 s41, 29
	s_cbranch_scc0 .LBB0_300
	s_and_b64 vcc, exec, s[52:53]
	s_cbranch_vccz .LBB0_303
	s_barrier

.LBB0_307:
	s_lshl_b32 s27, s20, 8
	s_add_i32 s0, s27, s77
	v_and_or_b32 v192, v2, 15, s0
	s_lshl_b32 s0, s56, 8
	s_ashr_i32 s1, s0, 31
	v_ashrrev_i32_e32 v0, 4, v2
	s_lshl_b64 s[0:1], s[0:1], 2
	v_lshlrev_b32_e32 v194, 3, v0
	s_add_u32 s0, s66, s0
	s_addc_u32 s1, s67, s1
	v_ashrrev_i32_e32 v195, 31, v194
	v_ashrrev_i32_e32 v193, 31, v192
	v_or_b32_e32 v206, 16, v192
	v_or_b32_e32 v208, 32, v192
	v_or_b32_e32 v210, 48, v192
	v_lshl_add_u64 v[6:7], v[194:195], 2, s[0:1]
	v_lshl_add_u64 v[146:147], v[192:193], 2, s[86:87]
	v_ashrrev_i32_e32 v207, 31, v206
	v_ashrrev_i32_e32 v209, 31, v208
	v_ashrrev_i32_e32 v211, 31, v210
	v_mov_b64_e32 v[10:11], v[220:221]
	v_mov_b64_e32 v[12:13], v[222:223]
	v_mov_b64_e32 v[14:15], v[224:225]
	v_mov_b64_e32 v[16:17], v[226:227]
	v_mov_b64_e32 v[2:3], v[228:229]
	v_mov_b64_e32 v[4:5], v[230:231]
	s_nop 0
	v_mov_b64_e32 v[6:7], v[232:233]
	v_mov_b64_e32 v[8:9], v[234:235]
	v_lshl_add_u64 v[148:149], v[206:207], 2, s[86:87]
	v_lshl_add_u64 v[150:151], v[208:209], 2, s[86:87]
	v_lshl_add_u64 v[152:153], v[210:211], 2, s[86:87]
	v_mov_b32_e32 v190, v236
	v_mov_b32_e32 v188, v237
	v_mov_b32_e32 v186, v238
	v_mov_b32_e32 v182, v239
	v_mov_b32_e32 v180, v240
	v_mov_b32_e32 v178, v241
	v_mov_b32_e32 v176, v242
	v_mov_b32_e32 v174, v243
	s_lshl_b32 s0, s18, 8
	s_ashr_i32 s31, s30, 31
	s_and_b32 s19, s0, 0x700
	s_lshl_b64 s[0:1], s[30:31], 25
	v_readlane_b32 s28, v251, 30
	s_add_u32 s0, s28, s0
	v_readlane_b32 s28, v251, 31
	v_add_u32_e32 v184, 0x80, v192
	v_add_u32_e32 v212, 0x90, v192
	v_add_u32_e32 v204, 0xa0, v192
	v_add_u32_e32 v202, 0xb0, v192
	s_addc_u32 s1, s28, s1
	s_or_b32 s19, s19, s14
	v_ashrrev_i32_e32 v185, 31, v184
	v_ashrrev_i32_e32 v213, 31, v212
	v_ashrrev_i32_e32 v205, 31, v204
	v_ashrrev_i32_e32 v203, 31, v202
	v_add_u32_e32 v200, s19, v194
	s_mov_b64 s[34:35], -1
	s_mov_b64 s[28:29], 0
	s_cmp_lt_i32 s49, 3
	s_mov_b64 s[42:43], 0
	s_cbranch_scc1 .LBB0_347
	s_cmp_gt_i32 s49, 3
	s_cbranch_scc0 .LBB0_344
	s_cmp_eq_u32 s49, 4
	s_mov_b64 s[42:43], -1
	s_cbranch_scc0 .LBB0_343
	v_cvt_f32_i32_e32 v147, v127
	v_cvt_f32_i32_e32 v146, v126
	v_cvt_f32_i32_e32 v151, v129
	v_cvt_f32_i32_e32 v150, v128
	v_readlane_b32 s34, v255, 14
	v_pk_mul_f32 v[148:149], v[190:191], v[6:7] op_sel_hi:[0,1]
	v_readlane_b32 s35, v255, 15
	v_pk_mul_f32 v[146:147], v[148:149], v[146:147]
	v_pk_mul_f32 v[148:149], v[190:191], v[8:9] op_sel_hi:[0,1]
	v_cndmask_b32_e64 v152, 0, 1, s[34:35]
	v_cmp_ne_u32_e64 s[42:43], 1, v152
	s_andn2_b64 vcc, exec, s[34:35]
	v_pk_mul_f32 v[148:149], v[148:149], v[150:151]
	s_cbranch_vccnz .LBB0_312
	v_mul_f32_e32 v150, 0xbfb8aa3b, v146
	v_mul_f32_e32 v151, 0xbfb8aa3b, v147
	v_mul_f32_e32 v152, 0xbfb8aa3b, v148
	v_mul_f32_e32 v153, 0xbfb8aa3b, v149
	v_exp_f32_e32 v150, v150
	v_exp_f32_e32 v151, v151
	v_exp_f32_e32 v152, v152
	v_exp_f32_e32 v153, v153
	v_add_f32_e32 v150, 1.0, v150
	v_add_f32_e32 v151, 1.0, v151
	v_add_f32_e32 v152, 1.0, v152
	v_add_f32_e32 v153, 1.0, v153
	v_rcp_f32_e32 v150, v150
	v_rcp_f32_e32 v151, v151
	v_rcp_f32_e32 v152, v152
	v_rcp_f32_e32 v153, v153
	v_pk_mul_f32 v[146:147], v[146:147], v[150:151]
	v_pk_mul_f32 v[148:149], v[148:149], v[152:153]
